# static s_setprio 1 for waves 4-7 during P3 attention queue
# baseline (speedup 1.0000x reference)
.LBB0_322:
	s_or_b64 exec, exec, s[4:5]
	v_lshrrev_b32_e32 v8, 5, v2
	v_lshlrev_b32_e32 v182, 2, v8
	v_and_b32_e32 v183, 31, v178
	v_or_b32_e32 v214, 3, v182
	v_cmp_lt_u32_e64 s[6:7], v214, v183
	v_or_b32_e32 v215, 8, v182
	v_or_b32_e32 v216, 9, v182
	v_writelane_b32 v254, s6, 50
	v_or_b32_e32 v217, 10, v182
	v_or_b32_e32 v218, 11, v182
	v_writelane_b32 v254, s7, 51
	v_cmp_lt_u32_e64 s[6:7], v215, v183
	v_or_b32_e32 v219, 16, v182
	v_or_b32_e32 v220, 17, v182
	v_writelane_b32 v254, s6, 52
	v_or_b32_e32 v221, 18, v182
	v_or_b32_e32 v222, 19, v182
	v_writelane_b32 v254, s7, 53
	v_cmp_lt_u32_e64 s[6:7], v216, v183
	s_mov_b32 s63, s15
	v_or_b32_e32 v223, 24, v182
	v_writelane_b32 v254, s6, 54
	s_lshl_b64 s[4:5], s[62:63], 2
	v_lshrrev_b32_e32 v10, 3, v178
	v_writelane_b32 v254, s7, 55
	v_cmp_lt_u32_e64 s[6:7], v217, v183
	s_add_u32 s24, s30, s4
	v_lshlrev_b32_e32 v176, 3, v8
	v_writelane_b32 v254, s6, 56
	v_lshlrev_b32_e32 v210, 4, v8
	v_and_b32_e32 v10, 4, v10
	v_writelane_b32 v254, s7, 57
	v_cmp_lt_u32_e64 s[6:7], v218, v183
	v_bfe_u32 v11, v178, 2, 2
	v_or_b32_e32 v224, 25, v182
	v_writelane_b32 v254, s6, 58
	v_lshrrev_b32_e32 v8, 1, v178
	s_addc_u32 s25, s31, s5
	v_writelane_b32 v254, s7, 59
	v_cmp_lt_u32_e64 s[6:7], v219, v183
	s_lshl_b32 s46, s14, 5
	v_and_b32_e32 v14, 16, v178
	v_writelane_b32 v254, s6, 60
	v_lshlrev_b32_e32 v2, 2, v2
	v_and_b32_e32 v227, 16, v8
	v_writelane_b32 v254, s7, 61
	v_cmp_lt_u32_e64 s[6:7], v220, v183
	v_or_b32_e32 v8, v11, v10
	v_and_or_b32 v2, v2, 12, v14
	v_writelane_b32 v254, s6, 62
	v_or_b32_e32 v225, 26, v182
	s_add_i32 s4, s46, 32
	v_writelane_b32 v254, s7, 63
	v_cmp_lt_u32_e64 s[6:7], v221, v183
	v_or_b32_e32 v14, 16, v8
	v_lshlrev_b32_e32 v211, 1, v2
	v_writelane_b32 v255, s6, 0
	v_or_b32_e32 v2, s4, v183
	v_or_b32_e32 v15, s4, v8
	v_writelane_b32 v255, s7, 1
	v_cmp_lt_u32_e64 s[6:7], v222, v183
	v_or_b32_e32 v16, s4, v14
	s_add_i32 s4, s46, 64
	v_writelane_b32 v255, s6, 2
	v_or_b32_e32 v226, 27, v182
	v_or_b32_e32 v17, s4, v8
	v_writelane_b32 v255, s7, 3
	v_cmp_lt_u32_e64 s[6:7], v223, v183
	v_or_b32_e32 v18, s4, v14
	s_add_i32 s4, s46, 0x60
	v_writelane_b32 v255, s6, 4
	v_or_b32_e32 v209, s46, v183
	v_or_b32_e32 v19, s4, v8
	v_writelane_b32 v255, s7, 5
	v_cmp_lt_u32_e64 s[6:7], v224, v183
	v_or_b32_e32 v14, s4, v14
	s_add_i32 s4, s46, 0x80
	v_writelane_b32 v255, s6, 6
	v_ashrrev_i32_e32 v205, 3, v178
	s_movk_i32 s5, 0x90
	v_writelane_b32 v255, s7, 7
	v_cmp_lt_u32_e64 s[6:7], v225, v183
	v_subrev_u32_e32 v20, s46, v209
	v_or_b32_e32 v21, s4, v183
	v_writelane_b32 v255, s6, 8
	v_or3_b32 v22, v10, s4, v11
	s_add_i32 s4, s46, 0x90
	v_writelane_b32 v255, s7, 9
	v_cmp_lt_u32_e64 s[6:7], v226, v183
	v_mul_lo_u32 v207, v205, s5
	v_mul_lo_u32 v9, v209, s5
	v_writelane_b32 v255, s6, 10
	v_or3_b32 v12, v10, s46, v11
	v_mul_lo_u32 v2, v2, s5
	v_writelane_b32 v255, s7, 11
	v_mul_lo_u32 v21, v21, s5
	v_or3_b32 v10, s4, v10, v11
	v_cmp_gt_i32_e64 s[4:5], v182, v20
	v_or_b32_e32 v213, 2, v182
	v_xor_b32_e32 v4, 32, v198
	v_writelane_b32 v255, s4, 12
	v_add_u32_e32 v0, 64, v0
	v_cmp_lt_i32_e32 vcc, v4, v0
	v_writelane_b32 v255, s5, 13
	v_cmp_gt_i32_e64 s[4:5], v213, v20
	v_cndmask_b32_e32 v0, v198, v4, vcc
	v_lshlrev_b32_e32 v179, 2, v0
	v_writelane_b32 v255, s4, 14
	v_lshlrev_b32_e32 v0, 4, v178
	v_mul_u32_u24_e32 v230, 0xc0, v8
	v_writelane_b32 v255, s5, 15
	v_cmp_gt_i32_e64 s[4:5], v214, v20
	v_and_b32_e32 v8, 3, v178
	v_and_b32_e32 v0, 0x70, v0
	v_writelane_b32 v255, s4, 16
	v_mul_lo_u32 v208, v205, s23
	v_mul_lo_u32 v12, v12, s23
	v_writelane_b32 v255, s5, 17
	v_cmp_gt_i32_e64 s[4:5], v215, v20
	v_mul_lo_u32 v15, v15, s23
	v_mul_lo_u32 v16, v16, s23
	v_writelane_b32 v255, s4, 18
	v_mul_lo_u32 v17, v17, s23
	v_mul_lo_u32 v18, v18, s23
	v_writelane_b32 v255, s5, 19
	v_cmp_gt_i32_e64 s[4:5], v216, v20
	v_mul_lo_u32 v19, v19, s23
	v_mul_lo_u32 v14, v14, s23
	v_writelane_b32 v255, s4, 20
	v_mul_lo_u32 v22, v22, s23
	v_mul_lo_u32 v10, v10, s23
	v_writelane_b32 v255, s5, 21
	v_cmp_gt_i32_e64 s[4:5], v217, v20
	v_and_b32_e32 v3, 32, v3
	v_lshlrev_b32_e32 v8, 3, v8
	v_lshl_add_u64 v[180:181], s[0:1], 0, v[0:1]
	v_add_u32_e32 v206, 0, v0
	v_add_u32_e32 v0, 0x3000, v208
	v_add_u32_e32 v4, 0x6000, v208
	v_add_u32_e32 v5, 0x9000, v208
	v_add_u32_e32 v6, 0xc000, v208
	v_add_u32_e32 v7, 0xf000, v208
	v_add_u32_e32 v9, 0, v9
	v_add_u32_e32 v13, 0, v12
	v_or_b32_e32 v212, 1, v182
	v_add_u32_e32 v2, 0, v2
	v_add_u32_e32 v15, 0, v15
	v_add_u32_e32 v16, 0, v16
	v_add_u32_e32 v17, 0, v17
	v_add_u32_e32 v18, 0, v18
	v_add_u32_e32 v19, 0, v19
	v_add_u32_e32 v14, 0, v14
	v_add_u32_e32 v21, 0, v21
	v_add_u32_e32 v22, 0, v22
	v_add_u32_e32 v10, 0, v10
	v_writelane_b32 v255, s4, 22
	s_movk_i32 s6, 0x80
	v_mul_u32_u24_e32 v229, 0x90, v183
	v_or3_b32 v231, v12, v3, v8
	s_mulk_i32 s14, 0x1200
	v_max_i32_e32 v3, 0x80, v209
	s_mov_b32 s70, s62
	v_cmp_lt_u32_e64 s[72:73], v182, v183
	v_cmp_lt_u32_e64 s[74:75], v212, v183
	v_cmp_lt_u32_e64 s[78:79], v213, v183
	v_cmp_lt_i32_e64 s[44:45], v182, v20
	v_writelane_b32 v255, s5, 23
	v_cmp_gt_i32_e64 s[56:57], v218, v20
	v_cmp_gt_i32_e64 s[58:59], v219, v20
	v_cmp_gt_i32_e64 s[60:61], v220, v20
	v_cmp_gt_i32_e64 s[62:63], v221, v20
	v_cmp_gt_i32_e64 s[64:65], v222, v20
	v_cmp_gt_i32_e64 s[66:67], v223, v20
	v_cmp_gt_i32_e64 s[40:41], v224, v20
	v_cmp_gt_i32_e64 s[8:9], v225, v20
	v_cmp_gt_i32_e64 s[4:5], v226, v20
	v_cmp_gt_i32_e64 s[6:7], s6, v178
	v_lshlrev_b32_e32 v228, 3, v178
	v_add3_u32 v232, s14, v229, v210
	v_subrev_u32_e32 v233, s46, v3
	s_or_b32 s71, s46, 31
	v_add_u32_e32 v196, v206, v0
	v_add_u32_e32 v202, v206, v4
	v_add_u32_e32 v203, v206, v5
	v_add_u32_e32 v204, v206, v6
	v_add_u32_e32 v238, v206, v7
	v_add_u32_e32 v239, v9, v210
	v_add_u32_e32 v240, v13, v211
	v_add_u32_e32 v241, v2, v227
	v_add_u32_e32 v242, v15, v211
	v_add_u32_e32 v243, v16, v211
	v_add_u32_e32 v244, v17, v211
	v_add_u32_e32 v245, v18, v211
	v_add_u32_e32 v246, v19, v211
	v_add_u32_e32 v247, v14, v211
	v_add_u32_e32 v248, v21, v210
	v_add_u32_e32 v249, v22, v211
	v_add_u32_e32 v250, v10, v211
	s_waitcnt lgkmcnt(0)
	s_barrier
	v_readfirstlane_b32 s10, v194
	s_cmpk_lt_u32 s10, 0x100
	s_cbranch_scc1 .Lprio_skip
	s_setprio 1
.Lprio_skip:
	s_mov_b32 s32, 0
	s_branch .LBB0_325

.LBB0_409:
	s_setprio 0
	v_readlane_b32 s4, v254, 49
	s_add_i32 s14, s4, 4
	v_readlane_b32 s4, v252, 9
	v_readlane_b32 s5, v252, 10
	s_cmp_ge_i32 s14, s5
	s_cbranch_scc1 .LBB0_421
	s_waitcnt vmcnt(0)
	s_barrier
	s_mov_b64 s[4:5], exec
	v_readlane_b32 s6, v252, 31
	v_readlane_b32 s7, v252, 32
	s_and_b64 s[6:7], s[4:5], s[6:7]
	s_mov_b32 s53, 0x2aaaaaab
	s_mov_b32 s62, s70
	s_mov_b64 exec, s[6:7]
	s_cbranch_execz .LBB0_463
	v_readlane_b32 s6, v254, 38
	s_waitcnt vmcnt(0) expcnt(0) lgkmcnt(0)
	s_nop 0
	v_mov_b32_e32 v0, s6
	ds_read_b32 v3, v0
	v_readlane_b32 s6, v254, 39
	s_waitcnt lgkmcnt(0)
	v_cmp_ne_u32_e32 vcc, 0, v3
	v_mov_b32_e32 v0, s6
	ds_read_b32 v2, v0
	s_cbranch_vccnz .LBB0_427
	s_mov_b32 s24, 1
	s_branch .LBB0_414
